# attention unit ids bit-permuted so each XCD's workgroups share K/V blocks (16 adjacent query blocks x both head pairs of one kv head per XCD) for L2 reuse; on v65
# baseline (speedup 1.0000x reference)
; #define LAS __attribute__((address_space(3)))
; __device__ __forceinline__ void attn_unit(const bf16* proj, unsigned char* ws, LAS unsigned char* lds, int a) {
;     int tid = threadIdx.x; asm volatile("" : "+v"(tid)); const int lane = tid & 63, wave = __builtin_amdgcn_readfirstlane(tid >> 6);
;     const float* par = (const float*)(ws + WS_PAR);
;     bf16* mix = (bf16*)(ws + WS_MIX); float* ssmix = (float*)(ws + WS_SSMIX);
;     const int gb = a >> 2, kvh = (a >> 1) & 1, hp = a & 1;
;     int n, nb; if (gb < 64) { nb = 32; n = gb & 31; } else { nb = 16; n = (gb - 64) & 15; }
;     const int tok0 = gb * 128, hw = wave >> 2, rq = wave & 3, fr = lane & 15, fq = lane >> 4;
;     const int h0 = kvh * 4 + hp * 2, h = h0 + hw;
;     LAS unsigned char* QS = lds + LQ; LAS unsigned char* KS = lds + LK; LAS unsigned char* VS = lds + LV;
;     const int kb0 = (n > 0) ? n - 1 : 0, kb1 = (n + 1 < nb) ? n + 1 : nb - 1;
;     v4u kr[4], vr[4];
;     {
;         v4u q0[4], q1[4];
;         tile_ld(q0, proj, tok0, C_Q + h0 * 128, tid); tile_ld(q1, proj, tok0, C_Q + (h0 + 1) * 128, tid);
;         tile_ld(kr, proj, tok0 + (kb0 - n) * 128, C_K + kvh * 128, tid); tile_ld(vr, proj, tok0 + (kb0 - n) * 128, C_V + kvh * 128, tid);
;         __syncthreads();
;         tile_st<QK_STRIDE>(q0, QS, tid); tile_st<QK_STRIDE>(q1, QS + 128 * QK_STRIDE, tid);
;     }
;     const LAS unsigned char* qbase = QS + hw * (128 * QK_STRIDE) + (rq * 32 + fr) * QK_STRIDE + (8 * fq) * 2;
;     const float sk2 = par[PAR_SINK + h] * LOG2E;
.LBB0_603:
	s_bfe_u32 s74, s68, 0x10003
	s_bfe_u32 s75, s68, 0x10000
	s_lshl_b32 s75, s75, 1
	s_or_b32 s74, s74, s75
	s_bfe_u32 s75, s68, 0x40004
	s_lshl_b32 s75, s75, 2
	s_or_b32 s74, s74, s75
	s_bfe_u32 s75, s68, 0x20001
	s_lshl_b32 s75, s75, 6
	s_or_b32 s74, s74, s75
	s_and_b32 s75, s68, 0x100
	s_or_b32 s76, s74, s75
	s_nop 0
	s_ashr_i32 s4, s76, 2
	s_bfe_u32 s5, s76, 0x10001
	s_cmp_lt_i32 s4, 64
	v_mov_b32_e32 v33, v160
	s_cselect_b32 s13, 31, 15
	s_lshl_b32 s3, s76, 1
	s_lshl_b32 s2, s5, 2
	v_readfirstlane_b32 s1, v33
	s_and_b32 s3, s3, 2
	s_and_b32 s69, s13, s4
	s_ashr_i32 s0, s1, 8
	s_or_b32 s2, s2, s3
	s_lshl_b32 s44, s4, 7
	s_add_i32 s50, s0, s2
	s_ashr_i32 s73, s50, 31
	s_mov_b32 s72, s50
	s_lshl_b64 s[72:73], s[72:73], 2
	s_add_u32 s72, s28, s72
	s_addc_u32 s73, s29, s73
	v_mov_b32_e32 v47, 0x200000
	global_load_dword v49, v47, s[72:73] offset:1024
	s_add_i32 s51, s69, 1
	s_lshl_b32 s2, s2, 8
	v_ashrrev_i32_e32 v34, 4, v33
	s_add_u32 s2, s26, s2
	v_lshlrev_b32_e32 v0, 4, v33
	v_add_u32_e32 v48, s44, v34
	s_addc_u32 s3, s27, 0
	v_and_b32_e32 v162, 0xf0, v0
	s_waitcnt lgkmcnt(0)
	v_lshl_add_u64 v[0:1], s[2:3], 0, v[162:163]
	v_add_u32_e32 v4, 32, v48
	v_add_u32_e32 v6, 64, v48
	v_add_u32_e32 v8, 0x60, v48
	v_mad_i64_i32 v[2:3], s[2:3], v48, s60, v[0:1]
	v_mad_i64_i32 v[4:5], s[2:3], v4, s60, v[0:1]
	v_mad_i64_i32 v[6:7], s[2:3], v6, s60, v[0:1]
	v_mad_i64_i32 v[0:1], s[2:3], v8, s60, v[0:1]
	v_sub_u32_e64 v35, s69, 1 clamp
	s_sub_i32 s2, s4, s69
	global_load_dwordx4 v[38:41], v[2:3], off
	global_load_dwordx4 v[42:45], v[2:3], off offset:256
	global_load_dwordx4 v[50:53], v[4:5], off
	global_load_dwordx4 v[54:57], v[4:5], off offset:256
	global_load_dwordx4 v[58:61], v[6:7], off
	global_load_dwordx4 v[62:65], v[6:7], off offset:256
	global_load_dwordx4 v[66:69], v[0:1], off
	global_load_dwordx4 v[70:73], v[0:1], off offset:256
	v_add_u32_e32 v0, s2, v35
	s_lshl_b32 s2, s5, 8
	s_add_u32 s2, s26, s2
	v_lshl_add_u32 v0, v0, 7, v34
	s_addc_u32 s3, s27, 0
	v_lshl_add_u64 v[164:165], s[2:3], 0, v[162:163]
	v_add_u32_e32 v1, 32, v0
	v_mad_i64_i32 v[4:5], s[2:3], v0, s60, v[164:165]
	v_mad_i64_i32 v[12:13], s[2:3], v1, s60, v[164:165]
	v_add_u32_e32 v1, 64, v0
	v_add_u32_e32 v0, 0x60, v0
	v_mad_i64_i32 v[20:21], s[2:3], v1, s60, v[164:165]
	s_waitcnt vmcnt(24)
	v_mad_i64_i32 v[28:29], s[2:3], v0, s60, v[164:165]
	global_load_dwordx4 v[0:3], v[4:5], off offset:2048
	s_nop 0
	global_load_dwordx4 v[4:7], v[4:5], off offset:2560
	s_nop 0
	global_load_dwordx4 v[8:11], v[12:13], off offset:2048
	s_nop 0
	global_load_dwordx4 v[12:15], v[12:13], off offset:2560
	s_nop 0
	global_load_dwordx4 v[16:19], v[20:21], off offset:2048
	s_nop 0
	global_load_dwordx4 v[20:23], v[20:21], off offset:2560
	s_nop 0
	global_load_dwordx4 v[24:27], v[28:29], off offset:2048
	s_nop 0
	global_load_dwordx4 v[28:31], v[28:29], off offset:2560
	v_bfe_u32 v37, v33, 4, 2
	s_lshr_b32 s1, s1, 1
	s_min_u32 s71, s51, s13
	v_and_b32_e32 v36, 15, v33
	v_mul_lo_u32 v32, v34, s64
	v_cmp_eq_u32_e64 s[2:3], 0, v37
	s_and_b32 s1, s1, 0x60
	v_cmp_ge_u32_e32 vcc, s71, v35
	v_cndmask_b32_e64 v174, 0, 1.0, s[2:3]
	v_add3_u32 v46, 0, v162, v32
	v_readfirstlane_b32 s70, v35
	v_or_b32_e32 v172, s1, v36
	s_mov_b64 s[4:5], -1
	s_and_b64 vcc, exec, vcc
	v_lshlrev_b32_e32 v175, 2, v37
	s_barrier
	s_waitcnt vmcnt(15)
	ds_write_b128 v46, v[38:41]
	s_waitcnt vmcnt(13)
	ds_write_b128 v46, v[50:53] offset:8704
	s_waitcnt vmcnt(11)
	ds_write_b128 v46, v[58:61] offset:17408
	s_waitcnt vmcnt(9)
	ds_write_b128 v46, v[66:69] offset:26112
	ds_write_b128 v46, v[42:45] offset:34816
	ds_write_b128 v46, v[54:57] offset:43520
	ds_write_b128 v46, v[62:65] offset:52224
	s_waitcnt vmcnt(8)
	ds_write_b128 v46, v[70:73] offset:60928
	s_cbranch_vccz .LBB0_615
; #define LAS __attribute__((address_space(3)))
; __device__ __forceinline__ void attn_unit(const bf16* proj, unsigned char* ws, LAS unsigned char* lds, int a) {
;     ...
;     const LAS unsigned char* qbase = QS + hw * (128 * QK_STRIDE) + (rq * 32 + fr) * QK_STRIDE + (8 * fq) * 2;
;     const float sk2 = par[PAR_SINK + h] * LOG2E;
;     float mrow[2], lrow[2]; mrow[0] = mrow[1] = sk2; lrow[0] = lrow[1] = (fq == 0) ? 1.0f : 0.0f;
;     f32x4 O[2][8];
; #pragma unroll
;     for (int rt = 0; rt < 2; ++rt)
; #pragma unroll
;         for (int dt = 0; dt < 8; ++dt) O[rt][dt] = (f32x4){0.f, 0.f, 0.f, 0.f};
	s_mul_i32 s0, s0, 0x8800
	s_ashr_i32 s51, s50, 31
	s_add_i32 s4, s0, 0
	s_lshl_b64 s[0:1], s[50:51], 2
	s_add_u32 s0, s28, s0
	s_addc_u32 s1, s29, s1
	v_mov_b32_e32 v35, 0x200000
	s_nop 0
	v_mbcnt_hi_u32_b32 v173, -1, v161
	v_and_b32_e32 v53, 64, v173
	v_lshlrev_b32_e32 v50, 4, v37
	v_xor_b32_e32 v178, 16, v173
	v_add_u32_e32 v180, 64, v53
	v_add_u32_e32 v35, s65, v162
	v_add_u32_e32 v38, s66, v162
	v_lshlrev_b32_e32 v162, 2, v37
	v_lshrrev_b32_e32 v37, 2, v36
	v_mul_u32_u24_e32 v51, 0x110, v36
	v_add_u32_e32 v52, s65, v50
	v_xor_b32_e32 v177, 32, v173
	v_cmp_lt_i32_e32 vcc, v178, v180
	v_lshlrev_b32_e32 v33, 3, v33
	v_or_b32_e32 v54, v162, v37
	v_mov_b32_e32 v56, s4
	v_add_u32_e32 v201, v52, v51
	v_cndmask_b32_e32 v52, v173, v178, vcc
	v_cmp_lt_i32_e32 vcc, v177, v180
	s_min_u32 s0, s69, 1
	v_mul_lo_u32 v34, v34, s62
	v_mov_b32_e32 v44, 0
	v_and_b32_e32 v55, 24, v33
	v_sub_u32_e32 v181, v162, v172
	v_mul_u32_u24_e32 v53, 0x120, v54
	v_mad_u32_u24 v51, v172, s64, v56
	v_cndmask_b32_e32 v54, v173, v177, vcc
	s_lshl_b32 s72, s0, 7
	s_mov_b32 s51, 0
	v_mov_b32_e32 v179, v174
	v_mov_b32_e32 v176, v174
	v_add_u32_e32 v182, v35, v32
	v_add_u32_e32 v183, v38, v34
	v_mov_b32_e32 v45, v44
	v_mov_b32_e32 v46, v44
	v_mov_b32_e32 v47, v44
	v_mov_b32_e32 v40, v44
	v_mov_b32_e32 v41, v44
	v_mov_b32_e32 v42, v44
	v_mov_b32_e32 v43, v44
	v_mov_b32_e32 v32, v44
	v_mov_b32_e32 v33, v44
	v_mov_b32_e32 v34, v44
	v_mov_b32_e32 v35, v44
	v_mov_b32_e32 v36, v44
	v_mov_b32_e32 v37, v44
	v_mov_b32_e32 v38, v44
	v_mov_b32_e32 v39, v44
	v_mov_b32_e32 v96, v44
	v_mov_b32_e32 v97, v44
	v_mov_b32_e32 v98, v44
	v_mov_b32_e32 v99, v44
	v_mov_b32_e32 v88, v44
	v_mov_b32_e32 v89, v44
	v_sub_u32_e32 v184, -2, v181
	v_add_u32_e32 v185, 0x70, v181
	v_sub_u32_e32 v186, 0xffffff90, v181
	v_add_u32_e32 v187, 0x71, v181
	v_sub_u32_e32 v188, 0xffffff8f, v181
	v_add_u32_e32 v189, 0x72, v181
	v_sub_u32_e32 v190, 0xffffff8e, v181
	v_add_u32_e32 v191, 0x73, v181
	v_sub_u32_e32 v192, 0xffffff8d, v181
	v_add_u32_e32 v193, -16, v181
	v_sub_u32_e32 v194, 16, v181
	v_add_u32_e32 v195, -15, v181
	v_sub_u32_e32 v196, 15, v181
	v_add_u32_e32 v197, -14, v181
	v_sub_u32_e32 v198, 14, v181
	v_add_u32_e32 v199, -13, v181
	v_sub_u32_e32 v200, 13, v181
	v_add3_u32 v202, s66, v55, v53
	v_lshlrev_b32_e32 v203, 2, v52
	v_lshlrev_b32_e32 v204, 2, v54
	v_add_u32_e32 v205, v51, v50
	v_subrev_u32_e32 v206, s72, v48
	v_mov_b32_e32 v90, v44
	v_mov_b32_e32 v91, v44
	v_mov_b32_e32 v80, v44
	s_waitcnt vmcnt(8)
	v_mul_f32_e32 v209, 0x3fb8aa3b, v49
	v_mov_b32_e32 v208, v209
	v_mov_b32_e32 v81, v44
	v_mov_b32_e32 v82, v44
	v_mov_b32_e32 v83, v44
	v_mov_b32_e32 v76, v44
	v_mov_b32_e32 v77, v44
	v_mov_b32_e32 v78, v44
	v_mov_b32_e32 v79, v44
	v_mov_b32_e32 v72, v44
	v_mov_b32_e32 v73, v44
	v_mov_b32_e32 v74, v44
	v_mov_b32_e32 v75, v44
	v_mov_b32_e32 v68, v44
	v_mov_b32_e32 v69, v44
	v_mov_b32_e32 v70, v44
	v_mov_b32_e32 v71, v44
	v_mov_b32_e32 v60, v44
	v_mov_b32_e32 v61, v44
	v_mov_b32_e32 v62, v44
	v_mov_b32_e32 v63, v44
	v_mov_b32_e32 v64, v44
	v_mov_b32_e32 v65, v44
	v_mov_b32_e32 v66, v44
	v_mov_b32_e32 v67, v44
	v_mov_b32_e32 v48, v44
	v_mov_b32_e32 v49, v44
	v_mov_b32_e32 v50, v44
	v_mov_b32_e32 v51, v44
	v_mov_b32_e32 v52, v44
	v_mov_b32_e32 v53, v44
	v_mov_b32_e32 v54, v44
	v_mov_b32_e32 v55, v44
	v_mov_b32_e32 v56, v44
	v_mov_b32_e32 v57, v44
	v_mov_b32_e32 v58, v44
	v_mov_b32_e32 v59, v44
	v_mov_b32_e32 v84, v44
	v_mov_b32_e32 v85, v44
	v_mov_b32_e32 v86, v44
	v_mov_b32_e32 v87, v44
	s_cmp_eq_u32 s51, 0
	s_cbranch_scc1 .LBB0_606
